# E24: E23 + per-layer RMSNorm row loop pipelined two rows deep (two prefetch register sets, loop unrolled by two)
# baseline (speedup 1.0000x reference)
; #define LAS __attribute__((address_space(3)))
; __device__ __forceinline__ unsigned cvt_pk_bf16(float lo, float hi) { f32x2_c v = {lo, hi}; bf16x2_c b = __builtin_convertvector(v, bf16x2_c); return __builtin_bit_cast(unsigned, b); }
; __global__ void __launch_bounds__(NWAVES * 64, 2) mk_fwd(Args args) {
;     ...
;             for (int i = tid; i < 2048; i += 512) { gL[i] = norm_w[l * 2048 + i] * (1.f + MODV[l * 6144 + 2048 + i]); sL[i] = MODV[l * 6144 + i]; }
;             __syncthreads();
;             for (int m = gw; m < SEQ; m += NGW) {
;                 const f32x4* xr = (const f32x4*)(xcur + (size_t)m * DMODEL) + lane;
;                 f32x4 v[8]; float s = 0.f;
; #pragma unroll
;                 for (int j = 0; j < 8; ++j) { v[j] = xr[64 * j]; s += (v[j][0] * v[j][0] + v[j][1] * v[j][1]) + (v[j][2] * v[j][2] + v[j][3] * v[j][3]); }
;                 const float rstd = __builtin_amdgcn_rsqf(wave_sum(s) * (1.f / DMODEL) + EPS);
;                 u32x2* o8 = (u32x2*)(Hb + (size_t)m * DMODEL) + lane;
; #pragma unroll
;                 for (int j = 0; j < 8; ++j) { const f32x4 g = *(const LAS f32x4*)(gL + 4 * lane + 256 * j), sh = *(const LAS f32x4*)(sL + 4 * lane + 256 * j);
;                     const f32x4 y = v[j] * rstd * g + sh; u32x2 w; w.x = cvt_pk_bf16(y[0], y[1]); w.y = cvt_pk_bf16(y[2], y[3]); o8[64 * j] = w; }
;             }
.LBB0_134:
	s_or_b64 exec, exec, s[4:5]
	s_ashr_i32 s1, s1, 6
	s_lshl_b32 s0, s0, 3
	s_add_i32 s4, s0, s1
	s_cmpk_gt_i32 s4, 0x3fff
	s_waitcnt lgkmcnt(0)
	s_barrier
	s_cbranch_scc1 .LBB0_137
	v_and_b32_e32 v66, 63, v0
	v_and_b32_e32 v0, 64, v252
	v_add_u32_e32 v0, 64, v0
	v_xor_b32_e32 v1, 1, v252
	v_cmp_lt_i32_e32 vcc, v1, v0
	v_lshlrev_b32_e32 v188, 4, v66
	v_add_u32_e32 v60, 0, v188
	v_cndmask_b32_e32 v1, v252, v1, vcc
	v_lshlrev_b32_e32 v100, 2, v1
	v_xor_b32_e32 v1, 2, v252
	v_cmp_lt_i32_e32 vcc, v1, v0
	s_add_u32 s0, s20, 0x20e00000
	s_addc_u32 s1, s21, 0
	v_cndmask_b32_e32 v1, v252, v1, vcc
	v_lshlrev_b32_e32 v101, 2, v1
	v_xor_b32_e32 v1, 4, v252
	v_cmp_lt_i32_e32 vcc, v1, v0
	s_cmp_eq_u32 s68, 0
	s_cselect_b32 s9, s9, s1
	v_cndmask_b32_e32 v1, v252, v1, vcc
	v_lshlrev_b32_e32 v102, 2, v1
	v_xor_b32_e32 v1, 8, v252
	v_cmp_lt_i32_e32 vcc, v1, v0
	s_cselect_b32 s8, s8, s0
	s_ashr_i32 s5, s4, 31
	v_cndmask_b32_e32 v1, v252, v1, vcc
	v_lshlrev_b32_e32 v103, 2, v1
	v_xor_b32_e32 v1, 16, v252
	v_cmp_lt_i32_e32 vcc, v1, v0
	s_lshl_b64 s[0:1], s[4:5], 13
	s_add_u32 s0, s8, s0
	v_cndmask_b32_e32 v1, v252, v1, vcc
	v_lshlrev_b32_e32 v104, 2, v1
	v_xor_b32_e32 v1, 32, v252
	v_cmp_lt_i32_e32 vcc, v1, v0
	s_addc_u32 s1, s9, s1
	v_lshl_add_u64 v[64:65], s[0:1], 0, v[188:189]
	v_cndmask_b32_e32 v0, v252, v1, vcc
	v_lshlrev_b32_e32 v105, 2, v0
	ds_read_b128 v[0:3], v60
	ds_read_b128 v[4:7], v60 offset:1024
	ds_read_b128 v[8:11], v60 offset:8192
	ds_read_b128 v[12:15], v60 offset:9216
	ds_read_b128 v[16:19], v60 offset:2048
	ds_read_b128 v[20:23], v60 offset:3072
	ds_read_b128 v[24:27], v60 offset:10240
	ds_read_b128 v[28:31], v60 offset:11264
	ds_read_b128 v[32:35], v60 offset:4096
	ds_read_b128 v[36:39], v60 offset:5120
	ds_read_b128 v[40:43], v60 offset:12288
	ds_read_b128 v[44:47], v60 offset:13312
	ds_read_b128 v[48:51], v60 offset:6144
	ds_read_b128 v[52:55], v60 offset:7168
	ds_read_b128 v[56:59], v60 offset:14336
	ds_read_b128 v[60:63], v60 offset:15360
	s_mov_b64 s[0:1], 0x1000
	v_lshl_add_u64 v[96:97], v[64:65], 0, s[0:1]
	s_lshl_b64 s[0:1], s[4:5], 12
	s_add_u32 s0, s6, s0
	s_addc_u32 s1, s7, s1
	v_readlane_b32 s5, v255, 18
	s_add_u32 s0, s5, s0
	v_readlane_b32 s5, v255, 19
	v_readlane_b32 s10, v255, 20
	v_lshlrev_b32_e32 v188, 3, v66
	s_addc_u32 s1, s5, s1
	v_readlane_b32 s11, v255, 21
	v_lshl_add_u64 v[98:99], s[0:1], 0, v[188:189]
	global_load_dwordx4 v[144:147], v[96:97], off offset:-4096
	global_load_dwordx4 v[140:143], v[96:97], off offset:-3072
	global_load_dwordx4 v[148:151], v[96:97], off offset:-2048
	global_load_dwordx4 v[152:155], v[96:97], off
	global_load_dwordx4 v[156:159], v[96:97], off offset:-1024
	global_load_dwordx4 v[160:163], v[96:97], off offset:1024
	global_load_dwordx4 v[164:167], v[96:97], off offset:3072
	global_load_dwordx4 v[168:171], v[96:97], off offset:2048
	v_lshl_add_u64 v[96:97], v[96:97], 0, s[60:61]
	s_add_i32 s99, s4, s58
	s_cmpk_gt_i32 s99, 0x3fff
	s_cbranch_scc1 .Ln2_pre_done
	global_load_dwordx4 v[194:197], v[96:97], off offset:-4096
	global_load_dwordx4 v[190:193], v[96:97], off offset:-3072
	global_load_dwordx4 v[198:201], v[96:97], off offset:-2048
	global_load_dwordx4 v[202:205], v[96:97], off
	global_load_dwordx4 v[206:209], v[96:97], off offset:-1024
	global_load_dwordx4 v[210:213], v[96:97], off offset:1024
	global_load_dwordx4 v[214:217], v[96:97], off offset:3072
	global_load_dwordx4 v[218:221], v[96:97], off offset:2048
	v_lshl_add_u64 v[96:97], v[96:97], 0, s[60:61]

; #define LAS __attribute__((address_space(3)))
; __device__ __forceinline__ unsigned cvt_pk_bf16(float lo, float hi) { f32x2_c v = {lo, hi}; bf16x2_c b = __builtin_convertvector(v, bf16x2_c); return __builtin_bit_cast(unsigned, b); }
; __global__ void __launch_bounds__(NWAVES * 64, 2) mk_fwd(Args args) {
;     ...
;             for (int m = gw; m < SEQ; m += NGW) {
;                 const f32x4* xr = (const f32x4*)(xcur + (size_t)m * DMODEL) + lane;
;                 f32x4 v[8]; float s = 0.f;
; #pragma unroll
;                 for (int j = 0; j < 8; ++j) { v[j] = xr[64 * j]; s += (v[j][0] * v[j][0] + v[j][1] * v[j][1]) + (v[j][2] * v[j][2] + v[j][3] * v[j][3]); }
;                 const float rstd = __builtin_amdgcn_rsqf(wave_sum(s) * (1.f / DMODEL) + EPS);
;                 u32x2* o8 = (u32x2*)(Hb + (size_t)m * DMODEL) + lane;
; #pragma unroll
;                 for (int j = 0; j < 8; ++j) { const f32x4 g = *(const LAS f32x4*)(gL + 4 * lane + 256 * j), sh = *(const LAS f32x4*)(sL + 4 * lane + 256 * j);
;                     const f32x4 y = v[j] * rstd * g + sh; u32x2 w; w.x = cvt_pk_bf16(y[0], y[1]); w.y = cvt_pk_bf16(y[2], y[3]); o8[64 * j] = w; }
;             }
.LBB0_136:
	s_add_i32 s4, s4, s58
	s_cmpk_gt_i32 s4, 0x3fff
	s_cbranch_scc1 .Ln2_e_w16
	s_waitcnt vmcnt(24)
	s_branch .Ln2_e_wd
.Ln2_e_w16:
	s_waitcnt vmcnt(16)
.Ln2_e_wd:
	v_mov_b64_e32 v[64:65], v[140:141]
	v_mov_b64_e32 v[66:67], v[142:143]
	v_mov_b64_e32 v[68:69], v[144:145]
	v_mov_b64_e32 v[70:71], v[146:147]
	v_mov_b64_e32 v[72:73], v[148:149]
	v_mov_b64_e32 v[74:75], v[150:151]
	v_mov_b64_e32 v[76:77], v[152:153]
	v_mov_b64_e32 v[78:79], v[154:155]
	v_mov_b64_e32 v[80:81], v[156:157]
	v_mov_b64_e32 v[82:83], v[158:159]
	v_mov_b64_e32 v[84:85], v[160:161]
	v_mov_b64_e32 v[86:87], v[162:163]
	v_mov_b64_e32 v[88:89], v[164:165]
	v_mov_b64_e32 v[90:91], v[166:167]
	v_mov_b64_e32 v[92:93], v[168:169]
	v_mov_b64_e32 v[94:95], v[170:171]
	s_add_i32 s99, s4, s58
	s_cmpk_gt_i32 s99, 0x3fff
	s_cbranch_scc1 .Ln2_e_nopf
	global_load_dwordx4 v[144:147], v[96:97], off offset:-4096
	global_load_dwordx4 v[140:143], v[96:97], off offset:-3072
	global_load_dwordx4 v[148:151], v[96:97], off offset:-2048
	global_load_dwordx4 v[152:155], v[96:97], off
	global_load_dwordx4 v[156:159], v[96:97], off offset:-1024
	global_load_dwordx4 v[160:163], v[96:97], off offset:1024
	global_load_dwordx4 v[164:167], v[96:97], off offset:3072
	global_load_dwordx4 v[168:171], v[96:97], off offset:2048
	v_lshl_add_u64 v[96:97], v[96:97], 0, s[60:61]
; #define LAS __attribute__((address_space(3)))
; __device__ __forceinline__ unsigned cvt_pk_bf16(float lo, float hi) { f32x2_c v = {lo, hi}; bf16x2_c b = __builtin_convertvector(v, bf16x2_c); return __builtin_bit_cast(unsigned, b); }
; __global__ void __launch_bounds__(NWAVES * 64, 2) mk_fwd(Args args) {
;     ...
;             for (int m = gw; m < SEQ; m += NGW) {
;                 const f32x4* xr = (const f32x4*)(xcur + (size_t)m * DMODEL) + lane;
;                 f32x4 v[8]; float s = 0.f;
; #pragma unroll
;                 for (int j = 0; j < 8; ++j) { v[j] = xr[64 * j]; s += (v[j][0] * v[j][0] + v[j][1] * v[j][1]) + (v[j][2] * v[j][2] + v[j][3] * v[j][3]); }
;                 const float rstd = __builtin_amdgcn_rsqf(wave_sum(s) * (1.f / DMODEL) + EPS);
;                 u32x2* o8 = (u32x2*)(Hb + (size_t)m * DMODEL) + lane;
; #pragma unroll
;                 for (int j = 0; j < 8; ++j) { const f32x4 g = *(const LAS f32x4*)(gL + 4 * lane + 256 * j), sh = *(const LAS f32x4*)(sL + 4 * lane + 256 * j);
;                     const f32x4 y = v[j] * rstd * g + sh; u32x2 w; w.x = cvt_pk_bf16(y[0], y[1]); w.y = cvt_pk_bf16(y[2], y[3]); o8[64 * j] = w; }
;             }
.Ln2_e_nopf:
	s_cmpk_gt_i32 s4, 0x3fff
	v_mov_b32_e32 v108, v69
	v_mov_b32_e32 v109, v65
	v_mov_b32_e32 v112, v71
	v_mov_b32_e32 v113, v67
	v_mov_b32_e32 v106, v68
	v_mov_b32_e32 v107, v64
	v_mov_b32_e32 v110, v70
	v_mov_b32_e32 v111, v66
	v_pk_mul_f32 v[114:115], v[74:75], v[74:75]
	v_pk_mul_f32 v[116:117], v[72:73], v[72:73]
	v_pk_mul_f32 v[108:109], v[108:109], v[108:109]
	v_pk_mul_f32 v[112:113], v[112:113], v[112:113]
	v_pk_mov_b32 v[130:131], v[116:117], v[114:115] op_sel:[1,0]
	v_mov_b32_e32 v117, v115
	v_pk_fma_f32 v[106:107], v[106:107], v[106:107], v[108:109]
	v_pk_fma_f32 v[108:109], v[110:111], v[110:111], v[112:113]
	v_mul_f32_e32 v118, v81, v81
	v_mul_f32_e32 v120, v83, v83
	v_pk_add_f32 v[110:111], v[130:131], v[116:117]
	v_pk_add_f32 v[106:107], v[106:107], v[108:109]
	v_mul_f32_e32 v129, v76, v76
	v_mul_f32_e32 v132, v77, v77
	v_mul_f32_e32 v133, v78, v78
	v_mul_f32_e32 v134, v79, v79
	v_pk_fma_f32 v[114:115], v[80:81], v[80:81], v[118:119] op_sel_hi:[1,1,0]
	v_pk_fma_f32 v[118:119], v[82:83], v[82:83], v[120:121] op_sel_hi:[1,1,0]
	v_pk_add_f32 v[108:109], v[110:111], v[110:111] op_sel:[0,1] op_sel_hi:[1,0]
	v_pk_add_f32 v[106:107], v[106:107], v[106:107] op_sel:[0,1] op_sel_hi:[1,0]
	v_pk_mul_f32 v[122:123], v[86:87], v[86:87]
	v_pk_mul_f32 v[124:125], v[84:85], v[84:85]
	v_mov_b32_e32 v115, v133
	v_mov_b32_e32 v119, v134
	v_mov_b32_e32 v109, v132
	v_mov_b32_e32 v107, v129
	v_pk_mov_b32 v[120:121], v[124:125], v[122:123] op_sel:[1,0]
	v_mov_b32_e32 v125, v123
	v_pk_add_f32 v[110:111], v[114:115], v[118:119]
	v_pk_add_f32 v[106:107], v[106:107], v[108:109]
	v_mul_f32_e32 v126, v93, v93
	v_mul_f32_e32 v128, v95, v95
	v_pk_add_f32 v[112:113], v[120:121], v[124:125]
	v_pk_add_f32 v[106:107], v[106:107], v[110:111]
	v_mul_f32_e32 v135, v88, v88
	v_mul_f32_e32 v136, v89, v89
	v_mul_f32_e32 v137, v90, v90
	v_mul_f32_e32 v138, v91, v91
	v_pk_fma_f32 v[122:123], v[92:93], v[92:93], v[126:127] op_sel_hi:[1,1,0]
	v_pk_fma_f32 v[126:127], v[94:95], v[94:95], v[128:129] op_sel_hi:[1,1,0]
	v_pk_add_f32 v[112:113], v[112:113], v[112:113] op_sel:[0,1] op_sel_hi:[1,0]
	v_pk_add_f32 v[106:107], v[106:107], v[106:107] op_sel:[0,1] op_sel_hi:[1,0]
	v_mov_b32_e32 v123, v137
	v_mov_b32_e32 v127, v138
	v_mov_b32_e32 v113, v136
	v_mov_b32_e32 v107, v135
	v_pk_add_f32 v[114:115], v[122:123], v[126:127]
	v_pk_add_f32 v[106:107], v[106:107], v[112:113]
	s_nop 0
	v_pk_add_f32 v[106:107], v[106:107], v[114:115]
	s_nop 0
	v_add_f32_e32 v106, v106, v107
	ds_bpermute_b32 v107, v100, v106
	s_waitcnt lgkmcnt(0)
	v_add_f32_e32 v106, v106, v107
	ds_bpermute_b32 v107, v101, v106
	s_waitcnt lgkmcnt(0)
	v_add_f32_e32 v106, v106, v107
	ds_bpermute_b32 v107, v102, v106
	s_waitcnt lgkmcnt(0)
	v_add_f32_e32 v106, v106, v107
	ds_bpermute_b32 v107, v103, v106
	s_waitcnt lgkmcnt(0)
	v_add_f32_e32 v106, v106, v107
	ds_bpermute_b32 v107, v104, v106
	s_waitcnt lgkmcnt(0)
	v_add_f32_e32 v106, v106, v107
	ds_bpermute_b32 v107, v105, v106
	s_waitcnt lgkmcnt(0)
	v_add_f32_e32 v106, v106, v107
	v_fmamk_f32 v106, v106, 0x3a000000, v253
	v_rsq_f32_e32 v106, v106
	s_nop 0
	v_pk_mul_f32 v[68:69], v[106:107], v[68:69] op_sel_hi:[0,1]
	v_pk_mul_f32 v[70:71], v[106:107], v[70:71] op_sel_hi:[0,1]
	v_pk_mul_f32 v[64:65], v[106:107], v[64:65] op_sel_hi:[0,1]
	v_pk_mul_f32 v[66:67], v[106:107], v[66:67] op_sel_hi:[0,1]
	v_pk_mul_f32 v[72:73], v[106:107], v[72:73] op_sel_hi:[0,1]
	v_pk_mul_f32 v[74:75], v[106:107], v[74:75] op_sel_hi:[0,1]
	v_pk_mul_f32 v[80:81], v[106:107], v[80:81] op_sel_hi:[0,1]
	v_pk_mul_f32 v[82:83], v[106:107], v[82:83] op_sel_hi:[0,1]
	v_pk_mul_f32 v[76:77], v[106:107], v[76:77] op_sel_hi:[0,1]
	v_pk_mul_f32 v[78:79], v[106:107], v[78:79] op_sel_hi:[0,1]
	v_pk_mul_f32 v[84:85], v[106:107], v[84:85] op_sel_hi:[0,1]
	v_pk_mul_f32 v[86:87], v[106:107], v[86:87] op_sel_hi:[0,1]
	v_pk_mul_f32 v[92:93], v[106:107], v[92:93] op_sel_hi:[0,1]
	v_pk_mul_f32 v[94:95], v[106:107], v[94:95] op_sel_hi:[0,1]
	v_pk_mul_f32 v[88:89], v[106:107], v[88:89] op_sel_hi:[0,1]
	v_pk_mul_f32 v[90:91], v[106:107], v[90:91] op_sel_hi:[0,1]
	v_pk_fma_f32 v[70:71], v[2:3], v[70:71], v[10:11]
	v_pk_fma_f32 v[68:69], v[0:1], v[68:69], v[8:9]
	v_pk_fma_f32 v[66:67], v[6:7], v[66:67], v[14:15]
	v_pk_fma_f32 v[64:65], v[4:5], v[64:65], v[12:13]
	v_pk_fma_f32 v[74:75], v[18:19], v[74:75], v[26:27]
	v_pk_fma_f32 v[72:73], v[16:17], v[72:73], v[24:25]
	v_pk_fma_f32 v[82:83], v[22:23], v[82:83], v[30:31]
	v_pk_fma_f32 v[80:81], v[20:21], v[80:81], v[28:29]
	v_pk_fma_f32 v[78:79], v[34:35], v[78:79], v[42:43]
	v_pk_fma_f32 v[76:77], v[32:33], v[76:77], v[40:41]
	v_pk_fma_f32 v[86:87], v[38:39], v[86:87], v[46:47]
	v_pk_fma_f32 v[84:85], v[36:37], v[84:85], v[44:45]
	v_pk_fma_f32 v[94:95], v[50:51], v[94:95], v[58:59]
	v_pk_fma_f32 v[92:93], v[48:49], v[92:93], v[56:57]
	v_pk_fma_f32 v[90:91], v[54:55], v[90:91], v[62:63]
	v_pk_fma_f32 v[88:89], v[52:53], v[88:89], v[60:61]
	v_cvt_pk_bf16_f32 v68, v68, v69
	v_cvt_pk_bf16_f32 v69, v70, v71
	v_cvt_pk_bf16_f32 v64, v64, v65
	v_cvt_pk_bf16_f32 v65, v66, v67
	v_cvt_pk_bf16_f32 v66, v72, v73
	v_cvt_pk_bf16_f32 v67, v74, v75
	v_cvt_pk_bf16_f32 v70, v80, v81
	v_cvt_pk_bf16_f32 v71, v82, v83
	v_cvt_pk_bf16_f32 v72, v76, v77
	v_cvt_pk_bf16_f32 v73, v78, v79
	v_cvt_pk_bf16_f32 v74, v84, v85
	v_cvt_pk_bf16_f32 v75, v86, v87
	v_cvt_pk_bf16_f32 v76, v92, v93
	v_cvt_pk_bf16_f32 v77, v94, v95
	v_cvt_pk_bf16_f32 v78, v88, v89
	v_cvt_pk_bf16_f32 v79, v90, v91
	global_store_dwordx2 v[98:99], v[68:69], off offset:-2048
	global_store_dwordx2 v[98:99], v[64:65], off offset:-1536
	global_store_dwordx2 v[98:99], v[66:67], off offset:-1024
	global_store_dwordx2 v[98:99], v[70:71], off offset:-512
	global_store_dwordx2 v[98:99], v[72:73], off
	global_store_dwordx2 v[98:99], v[74:75], off offset:512
	global_store_dwordx2 v[98:99], v[76:77], off offset:1024
	global_store_dwordx2 v[98:99], v[78:79], off offset:1536
	v_lshl_add_u64 v[98:99], v[98:99], 0, s[10:11]
	s_cbranch_scc1 .LBB0_137
	s_add_i32 s4, s4, s58
	s_cmpk_gt_i32 s4, 0x3fff
	s_cbranch_scc1 .Ln2_o_w16
	s_waitcnt vmcnt(24)
	s_branch .Ln2_o_wd

; #define LAS __attribute__((address_space(3)))
; __device__ __forceinline__ unsigned cvt_pk_bf16(float lo, float hi) { f32x2_c v = {lo, hi}; bf16x2_c b = __builtin_convertvector(v, bf16x2_c); return __builtin_bit_cast(unsigned, b); }
; __global__ void __launch_bounds__(NWAVES * 64, 2) mk_fwd(Args args) {
;     ...
;             for (int m = gw; m < SEQ; m += NGW) {
;                 const f32x4* xr = (const f32x4*)(xcur + (size_t)m * DMODEL) + lane;
;                 f32x4 v[8]; float s = 0.f;
; #pragma unroll
;                 for (int j = 0; j < 8; ++j) { v[j] = xr[64 * j]; s += (v[j][0] * v[j][0] + v[j][1] * v[j][1]) + (v[j][2] * v[j][2] + v[j][3] * v[j][3]); }
;                 const float rstd = __builtin_amdgcn_rsqf(wave_sum(s) * (1.f / DMODEL) + EPS);
;                 u32x2* o8 = (u32x2*)(Hb + (size_t)m * DMODEL) + lane;
; #pragma unroll
;                 for (int j = 0; j < 8; ++j) { const f32x4 g = *(const LAS f32x4*)(gL + 4 * lane + 256 * j), sh = *(const LAS f32x4*)(sL + 4 * lane + 256 * j);
;                     const f32x4 y = v[j] * rstd * g + sh; u32x2 w; w.x = cvt_pk_bf16(y[0], y[1]); w.y = cvt_pk_bf16(y[2], y[3]); o8[64 * j] = w; }
;             }
.Ln2_o_wd:
	v_mov_b64_e32 v[64:65], v[190:191]
	v_mov_b64_e32 v[66:67], v[192:193]
	v_mov_b64_e32 v[68:69], v[194:195]
	v_mov_b64_e32 v[70:71], v[196:197]
	v_mov_b64_e32 v[72:73], v[198:199]
	v_mov_b64_e32 v[74:75], v[200:201]
	v_mov_b64_e32 v[76:77], v[202:203]
	v_mov_b64_e32 v[78:79], v[204:205]
	v_mov_b64_e32 v[80:81], v[206:207]
	v_mov_b64_e32 v[82:83], v[208:209]
	v_mov_b64_e32 v[84:85], v[210:211]
	v_mov_b64_e32 v[86:87], v[212:213]
	v_mov_b64_e32 v[88:89], v[214:215]
	v_mov_b64_e32 v[90:91], v[216:217]
	v_mov_b64_e32 v[92:93], v[218:219]
	v_mov_b64_e32 v[94:95], v[220:221]
	s_add_i32 s99, s4, s58
	s_cmpk_gt_i32 s99, 0x3fff
	s_cbranch_scc1 .Ln2_o_nopf
	global_load_dwordx4 v[194:197], v[96:97], off offset:-4096
	global_load_dwordx4 v[190:193], v[96:97], off offset:-3072
	global_load_dwordx4 v[198:201], v[96:97], off offset:-2048
	global_load_dwordx4 v[202:205], v[96:97], off
	global_load_dwordx4 v[206:209], v[96:97], off offset:-1024
	global_load_dwordx4 v[210:213], v[96:97], off offset:1024
	global_load_dwordx4 v[214:217], v[96:97], off offset:3072
	global_load_dwordx4 v[218:221], v[96:97], off offset:2048
	v_lshl_add_u64 v[96:97], v[96:97], 0, s[60:61]
; #define LAS __attribute__((address_space(3)))
; __device__ __forceinline__ unsigned cvt_pk_bf16(float lo, float hi) { f32x2_c v = {lo, hi}; bf16x2_c b = __builtin_convertvector(v, bf16x2_c); return __builtin_bit_cast(unsigned, b); }
; __global__ void __launch_bounds__(NWAVES * 64, 2) mk_fwd(Args args) {
;     ...
;             for (int m = gw; m < SEQ; m += NGW) {
;                 const f32x4* xr = (const f32x4*)(xcur + (size_t)m * DMODEL) + lane;
;                 f32x4 v[8]; float s = 0.f;
; #pragma unroll
;                 for (int j = 0; j < 8; ++j) { v[j] = xr[64 * j]; s += (v[j][0] * v[j][0] + v[j][1] * v[j][1]) + (v[j][2] * v[j][2] + v[j][3] * v[j][3]); }
;                 const float rstd = __builtin_amdgcn_rsqf(wave_sum(s) * (1.f / DMODEL) + EPS);
;                 u32x2* o8 = (u32x2*)(Hb + (size_t)m * DMODEL) + lane;
; #pragma unroll
;                 for (int j = 0; j < 8; ++j) { const f32x4 g = *(const LAS f32x4*)(gL + 4 * lane + 256 * j), sh = *(const LAS f32x4*)(sL + 4 * lane + 256 * j);
;                     const f32x4 y = v[j] * rstd * g + sh; u32x2 w; w.x = cvt_pk_bf16(y[0], y[1]); w.y = cvt_pk_bf16(y[2], y[3]); o8[64 * j] = w; }
;             }
.Ln2_o_nopf:
	s_cmpk_gt_i32 s4, 0x3fff
	v_mov_b32_e32 v108, v69
	v_mov_b32_e32 v109, v65
	v_mov_b32_e32 v112, v71
	v_mov_b32_e32 v113, v67
	v_mov_b32_e32 v106, v68
	v_mov_b32_e32 v107, v64
	v_mov_b32_e32 v110, v70
	v_mov_b32_e32 v111, v66
	v_pk_mul_f32 v[114:115], v[74:75], v[74:75]
	v_pk_mul_f32 v[116:117], v[72:73], v[72:73]
	v_pk_mul_f32 v[108:109], v[108:109], v[108:109]
	v_pk_mul_f32 v[112:113], v[112:113], v[112:113]
	v_pk_mov_b32 v[130:131], v[116:117], v[114:115] op_sel:[1,0]
	v_mov_b32_e32 v117, v115
	v_pk_fma_f32 v[106:107], v[106:107], v[106:107], v[108:109]
	v_pk_fma_f32 v[108:109], v[110:111], v[110:111], v[112:113]
	v_mul_f32_e32 v118, v81, v81
	v_mul_f32_e32 v120, v83, v83
	v_pk_add_f32 v[110:111], v[130:131], v[116:117]
	v_pk_add_f32 v[106:107], v[106:107], v[108:109]
	v_mul_f32_e32 v129, v76, v76
	v_mul_f32_e32 v132, v77, v77
	v_mul_f32_e32 v133, v78, v78
	v_mul_f32_e32 v134, v79, v79
	v_pk_fma_f32 v[114:115], v[80:81], v[80:81], v[118:119] op_sel_hi:[1,1,0]
	v_pk_fma_f32 v[118:119], v[82:83], v[82:83], v[120:121] op_sel_hi:[1,1,0]
	v_pk_add_f32 v[108:109], v[110:111], v[110:111] op_sel:[0,1] op_sel_hi:[1,0]
	v_pk_add_f32 v[106:107], v[106:107], v[106:107] op_sel:[0,1] op_sel_hi:[1,0]
	v_pk_mul_f32 v[122:123], v[86:87], v[86:87]
	v_pk_mul_f32 v[124:125], v[84:85], v[84:85]
	v_mov_b32_e32 v115, v133
	v_mov_b32_e32 v119, v134
	v_mov_b32_e32 v109, v132
	v_mov_b32_e32 v107, v129
	v_pk_mov_b32 v[120:121], v[124:125], v[122:123] op_sel:[1,0]
	v_mov_b32_e32 v125, v123
	v_pk_add_f32 v[110:111], v[114:115], v[118:119]
	v_pk_add_f32 v[106:107], v[106:107], v[108:109]
	v_mul_f32_e32 v126, v93, v93
	v_mul_f32_e32 v128, v95, v95
	v_pk_add_f32 v[112:113], v[120:121], v[124:125]
	v_pk_add_f32 v[106:107], v[106:107], v[110:111]
	v_mul_f32_e32 v135, v88, v88
	v_mul_f32_e32 v136, v89, v89
	v_mul_f32_e32 v137, v90, v90
	v_mul_f32_e32 v138, v91, v91
	v_pk_fma_f32 v[122:123], v[92:93], v[92:93], v[126:127] op_sel_hi:[1,1,0]
	v_pk_fma_f32 v[126:127], v[94:95], v[94:95], v[128:129] op_sel_hi:[1,1,0]
	v_pk_add_f32 v[112:113], v[112:113], v[112:113] op_sel:[0,1] op_sel_hi:[1,0]
	v_pk_add_f32 v[106:107], v[106:107], v[106:107] op_sel:[0,1] op_sel_hi:[1,0]
	v_mov_b32_e32 v123, v137
	v_mov_b32_e32 v127, v138
	v_mov_b32_e32 v113, v136
	v_mov_b32_e32 v107, v135
	v_pk_add_f32 v[114:115], v[122:123], v[126:127]
	v_pk_add_f32 v[106:107], v[106:107], v[112:113]
	s_nop 0
	v_pk_add_f32 v[106:107], v[106:107], v[114:115]
	s_nop 0
	v_add_f32_e32 v106, v106, v107
	ds_bpermute_b32 v107, v100, v106
	s_waitcnt lgkmcnt(0)
	v_add_f32_e32 v106, v106, v107
	ds_bpermute_b32 v107, v101, v106
	s_waitcnt lgkmcnt(0)
	v_add_f32_e32 v106, v106, v107
	ds_bpermute_b32 v107, v102, v106
	s_waitcnt lgkmcnt(0)
	v_add_f32_e32 v106, v106, v107
	ds_bpermute_b32 v107, v103, v106
	s_waitcnt lgkmcnt(0)
	v_add_f32_e32 v106, v106, v107
	ds_bpermute_b32 v107, v104, v106
	s_waitcnt lgkmcnt(0)
	v_add_f32_e32 v106, v106, v107
	ds_bpermute_b32 v107, v105, v106
	s_waitcnt lgkmcnt(0)
	v_add_f32_e32 v106, v106, v107
	v_fmamk_f32 v106, v106, 0x3a000000, v253
	v_rsq_f32_e32 v106, v106
	s_nop 0
	v_pk_mul_f32 v[68:69], v[106:107], v[68:69] op_sel_hi:[0,1]
	v_pk_mul_f32 v[70:71], v[106:107], v[70:71] op_sel_hi:[0,1]
	v_pk_mul_f32 v[64:65], v[106:107], v[64:65] op_sel_hi:[0,1]
	v_pk_mul_f32 v[66:67], v[106:107], v[66:67] op_sel_hi:[0,1]
	v_pk_mul_f32 v[72:73], v[106:107], v[72:73] op_sel_hi:[0,1]
	v_pk_mul_f32 v[74:75], v[106:107], v[74:75] op_sel_hi:[0,1]
	v_pk_mul_f32 v[80:81], v[106:107], v[80:81] op_sel_hi:[0,1]
	v_pk_mul_f32 v[82:83], v[106:107], v[82:83] op_sel_hi:[0,1]
	v_pk_mul_f32 v[76:77], v[106:107], v[76:77] op_sel_hi:[0,1]
	v_pk_mul_f32 v[78:79], v[106:107], v[78:79] op_sel_hi:[0,1]
	v_pk_mul_f32 v[84:85], v[106:107], v[84:85] op_sel_hi:[0,1]
	v_pk_mul_f32 v[86:87], v[106:107], v[86:87] op_sel_hi:[0,1]
	v_pk_mul_f32 v[92:93], v[106:107], v[92:93] op_sel_hi:[0,1]
	v_pk_mul_f32 v[94:95], v[106:107], v[94:95] op_sel_hi:[0,1]
	v_pk_mul_f32 v[88:89], v[106:107], v[88:89] op_sel_hi:[0,1]
	v_pk_mul_f32 v[90:91], v[106:107], v[90:91] op_sel_hi:[0,1]
	v_pk_fma_f32 v[70:71], v[2:3], v[70:71], v[10:11]
	v_pk_fma_f32 v[68:69], v[0:1], v[68:69], v[8:9]
	v_pk_fma_f32 v[66:67], v[6:7], v[66:67], v[14:15]
	v_pk_fma_f32 v[64:65], v[4:5], v[64:65], v[12:13]
	v_pk_fma_f32 v[74:75], v[18:19], v[74:75], v[26:27]
	v_pk_fma_f32 v[72:73], v[16:17], v[72:73], v[24:25]
	v_pk_fma_f32 v[82:83], v[22:23], v[82:83], v[30:31]
	v_pk_fma_f32 v[80:81], v[20:21], v[80:81], v[28:29]
	v_pk_fma_f32 v[78:79], v[34:35], v[78:79], v[42:43]
	v_pk_fma_f32 v[76:77], v[32:33], v[76:77], v[40:41]
	v_pk_fma_f32 v[86:87], v[38:39], v[86:87], v[46:47]
	v_pk_fma_f32 v[84:85], v[36:37], v[84:85], v[44:45]
	v_pk_fma_f32 v[94:95], v[50:51], v[94:95], v[58:59]
	v_pk_fma_f32 v[92:93], v[48:49], v[92:93], v[56:57]
	v_pk_fma_f32 v[90:91], v[54:55], v[90:91], v[62:63]
	v_pk_fma_f32 v[88:89], v[52:53], v[88:89], v[60:61]
	v_cvt_pk_bf16_f32 v68, v68, v69
	v_cvt_pk_bf16_f32 v69, v70, v71
	v_cvt_pk_bf16_f32 v64, v64, v65
	v_cvt_pk_bf16_f32 v65, v66, v67
	v_cvt_pk_bf16_f32 v66, v72, v73
	v_cvt_pk_bf16_f32 v67, v74, v75
	v_cvt_pk_bf16_f32 v70, v80, v81
	v_cvt_pk_bf16_f32 v71, v82, v83
	v_cvt_pk_bf16_f32 v72, v76, v77
	v_cvt_pk_bf16_f32 v73, v78, v79
	v_cvt_pk_bf16_f32 v74, v84, v85
	v_cvt_pk_bf16_f32 v75, v86, v87
	v_cvt_pk_bf16_f32 v76, v92, v93
	v_cvt_pk_bf16_f32 v77, v94, v95
	v_cvt_pk_bf16_f32 v78, v88, v89
	v_cvt_pk_bf16_f32 v79, v90, v91
	global_store_dwordx2 v[98:99], v[68:69], off offset:-2048
	global_store_dwordx2 v[98:99], v[64:65], off offset:-1536
	global_store_dwordx2 v[98:99], v[66:67], off offset:-1024
	global_store_dwordx2 v[98:99], v[70:71], off offset:-512
	global_store_dwordx2 v[98:99], v[72:73], off
	global_store_dwordx2 v[98:99], v[74:75], off offset:512
	global_store_dwordx2 v[98:99], v[76:77], off offset:1024
	global_store_dwordx2 v[98:99], v[78:79], off offset:1536
	v_lshl_add_u64 v[98:99], v[98:99], 0, s[10:11]
	s_cbranch_scc0 .LBB0_136
